# mods phase: silu(c) staging loop with all 18 loads in flight instead of one round trip per element
# speedup vs baseline: 1.0924x; 1.0112x over previous
; __device__ __forceinline__ float siluf(float x) { return x * frcp(1.f + fexp(-x)); }
; __device__ void mods_phase(unsigned char* lds, const Params& p) {
;     ...
;   for (int tile = blockIdx.x; tile < 384; tile += gridDim.x) {
;     const int l = tile / 192, cb = (tile % 192) * 32;
;     for (int i = tid; i < 9 * 1024; i += 512) {
;       float v = (i < 8192) ? c[i] : cc[i - 8192];
;       sl[i] = siluf(v);
;     }
;     __syncthreads();
.LBB0_8:
	s_and_saveexec_b64 s[16:17], vcc
	s_load_dwordx16 s[44:59], s[0:1], 0x0
	s_cbranch_execz .LBB0_11
	s_waitcnt lgkmcnt(0)
	v_lshlrev_b32_e32 v26, 2, v134
	global_load_dword v8, v26, s[46:47]
	v_add_u32_e32 v27, 0x800, v26
	global_load_dword v9, v27, s[46:47]
	v_add_u32_e32 v27, 0x800, v27
	global_load_dword v10, v27, s[46:47]
	v_add_u32_e32 v27, 0x800, v27
	global_load_dword v11, v27, s[46:47]
	v_add_u32_e32 v27, 0x800, v27
	global_load_dword v12, v27, s[46:47]
	v_add_u32_e32 v27, 0x800, v27
	global_load_dword v13, v27, s[46:47]
	v_add_u32_e32 v27, 0x800, v27
	global_load_dword v14, v27, s[46:47]
	v_add_u32_e32 v27, 0x800, v27
	global_load_dword v15, v27, s[46:47]
	v_add_u32_e32 v27, 0x800, v27
	global_load_dword v16, v27, s[46:47]
	v_add_u32_e32 v27, 0x800, v27
	global_load_dword v17, v27, s[46:47]
	v_add_u32_e32 v27, 0x800, v27
	global_load_dword v18, v27, s[46:47]
	v_add_u32_e32 v27, 0x800, v27
	global_load_dword v19, v27, s[46:47]
	v_add_u32_e32 v27, 0x800, v27
	global_load_dword v20, v27, s[46:47]
	v_add_u32_e32 v27, 0x800, v27
	global_load_dword v21, v27, s[46:47]
	v_add_u32_e32 v27, 0x800, v27
	global_load_dword v22, v27, s[46:47]
	v_add_u32_e32 v27, 0x800, v27
	global_load_dword v23, v27, s[46:47]
	global_load_dword v24, v26, s[50:51]
	global_load_dword v25, v26, s[50:51] offset:2048
	s_waitcnt vmcnt(12)
	v_mul_f32_e32 v28, 0xbfb8aa3b, v8
	v_mul_f32_e32 v29, 0xbfb8aa3b, v9
	v_mul_f32_e32 v30, 0xbfb8aa3b, v10
	v_mul_f32_e32 v31, 0xbfb8aa3b, v11
	v_mul_f32_e32 v32, 0xbfb8aa3b, v12
	v_mul_f32_e32 v33, 0xbfb8aa3b, v13
	v_exp_f32_e32 v28, v28
	v_exp_f32_e32 v29, v29
	v_exp_f32_e32 v30, v30
	v_exp_f32_e32 v31, v31
	v_exp_f32_e32 v32, v32
	v_exp_f32_e32 v33, v33
	v_add_f32_e32 v28, 1.0, v28
	v_add_f32_e32 v29, 1.0, v29
	v_add_f32_e32 v30, 1.0, v30
	v_add_f32_e32 v31, 1.0, v31
	v_add_f32_e32 v32, 1.0, v32
	v_add_f32_e32 v33, 1.0, v33
	v_rcp_f32_e32 v28, v28
	v_rcp_f32_e32 v29, v29
	v_rcp_f32_e32 v30, v30
	v_rcp_f32_e32 v31, v31
	v_rcp_f32_e32 v32, v32
	v_rcp_f32_e32 v33, v33
	v_mul_f32_e32 v8, v8, v28
	v_mul_f32_e32 v9, v9, v29
	v_mul_f32_e32 v10, v10, v30
	v_mul_f32_e32 v11, v11, v31
	v_mul_f32_e32 v12, v12, v32
	v_mul_f32_e32 v13, v13, v33
	ds_write_b32 v155, v8
	ds_write_b32 v155, v9 offset:2048
	ds_write_b32 v155, v10 offset:4096
	ds_write_b32 v155, v11 offset:6144
	ds_write_b32 v155, v12 offset:8192
	ds_write_b32 v155, v13 offset:10240
	s_waitcnt vmcnt(6)
	v_mul_f32_e32 v28, 0xbfb8aa3b, v14
	v_mul_f32_e32 v29, 0xbfb8aa3b, v15
	v_mul_f32_e32 v30, 0xbfb8aa3b, v16
	v_mul_f32_e32 v31, 0xbfb8aa3b, v17
	v_mul_f32_e32 v32, 0xbfb8aa3b, v18
	v_mul_f32_e32 v33, 0xbfb8aa3b, v19
	v_exp_f32_e32 v28, v28
	v_exp_f32_e32 v29, v29
	v_exp_f32_e32 v30, v30
	v_exp_f32_e32 v31, v31
	v_exp_f32_e32 v32, v32
	v_exp_f32_e32 v33, v33
	v_add_f32_e32 v28, 1.0, v28
	v_add_f32_e32 v29, 1.0, v29
	v_add_f32_e32 v30, 1.0, v30
	v_add_f32_e32 v31, 1.0, v31
	v_add_f32_e32 v32, 1.0, v32
	v_add_f32_e32 v33, 1.0, v33
	v_rcp_f32_e32 v28, v28
	v_rcp_f32_e32 v29, v29
	v_rcp_f32_e32 v30, v30
	v_rcp_f32_e32 v31, v31
	v_rcp_f32_e32 v32, v32
	v_rcp_f32_e32 v33, v33
	v_mul_f32_e32 v14, v14, v28
	v_mul_f32_e32 v15, v15, v29
	v_mul_f32_e32 v16, v16, v30
	v_mul_f32_e32 v17, v17, v31
	v_mul_f32_e32 v18, v18, v32
	v_mul_f32_e32 v19, v19, v33
	ds_write_b32 v155, v14 offset:12288
	ds_write_b32 v155, v15 offset:14336
	ds_write_b32 v155, v16 offset:16384
	ds_write_b32 v155, v17 offset:18432
	ds_write_b32 v155, v18 offset:20480
	ds_write_b32 v155, v19 offset:22528
	s_waitcnt vmcnt(0)
	v_mul_f32_e32 v28, 0xbfb8aa3b, v20
	v_mul_f32_e32 v29, 0xbfb8aa3b, v21
	v_mul_f32_e32 v30, 0xbfb8aa3b, v22
	v_mul_f32_e32 v31, 0xbfb8aa3b, v23
	v_mul_f32_e32 v32, 0xbfb8aa3b, v24
	v_mul_f32_e32 v33, 0xbfb8aa3b, v25
	v_exp_f32_e32 v28, v28
	v_exp_f32_e32 v29, v29
	v_exp_f32_e32 v30, v30
	v_exp_f32_e32 v31, v31
	v_exp_f32_e32 v32, v32
	v_exp_f32_e32 v33, v33
	v_add_f32_e32 v28, 1.0, v28
	v_add_f32_e32 v29, 1.0, v29
	v_add_f32_e32 v30, 1.0, v30
	v_add_f32_e32 v31, 1.0, v31
	v_add_f32_e32 v32, 1.0, v32
	v_add_f32_e32 v33, 1.0, v33
	v_rcp_f32_e32 v28, v28
	v_rcp_f32_e32 v29, v29
	v_rcp_f32_e32 v30, v30
	v_rcp_f32_e32 v31, v31
	v_rcp_f32_e32 v32, v32
	v_rcp_f32_e32 v33, v33
	v_mul_f32_e32 v20, v20, v28
	v_mul_f32_e32 v21, v21, v29
	v_mul_f32_e32 v22, v22, v30
	v_mul_f32_e32 v23, v23, v31
	v_mul_f32_e32 v24, v24, v32
	v_mul_f32_e32 v25, v25, v33
	ds_write_b32 v155, v20 offset:24576
	ds_write_b32 v155, v21 offset:26624
	ds_write_b32 v155, v22 offset:28672
	ds_write_b32 v155, v23 offset:30720
	ds_write_b32 v155, v24 offset:32768
	ds_write_b32 v155, v25 offset:34816
